# v10 plus f1_unit LDS-to-D copy as straight-line code (9 ds_read_b128 up front, 9 stores), replaces branchy 9-iteration loop
# speedup vs baseline: 1.0097x; 1.0015x over previous
; __device__ __forceinline__ int opq(int x) { asm volatile("" : "+v"(x)); return x; }
; __device__ __forceinline__ float delta_prep(const Params& p, int l, int h, bool isP, int grow0, int t0, int nvalid, int bb, char* sm) {
;     ...
;   {
;     const float eg = misc[128 + rl];
;     const float ek = __expf(Glast - misc[rl]);
;     bfraw* qg = (bfraw*)(sm + L_QG);
;     bfraw* kgT = (bfraw*)(sm + L_KGT);
;     float t[16];
; #pragma unroll
;     for (int e = 0; e < 16; ++e) t[e] = qf[e] * eg;
;     *(uint4*)(qg + rl * 136 + cg8 * 16) = pack8(t); *(uint4*)(qg + rl * 136 + cg8 * 16 + 8) = pack8(t + 8);
; #pragma unroll
;     for (int e = 0; e < 16; ++e) kgT[(cg8 * 16 + e) * 72 + rl] = f2bf(kf[e] * ek);
;   }
;   const float gl = expf(Glast);
;   __syncthreads();
; __device__ __forceinline__ void f1_unit(const Params& p, int l, int u, char* sm) {
;     ...
;   bfraw* D = (bfraw*)(p.ws + WS_D) + (size_t)u * DUNIT;
;   for (int cidx = opq(threadIdx.x); cidx < 4608; cidx += NTHR)
;     *(uint4*)(D + (size_t)cidx * 8) = *(const uint4*)(sm + dchunk_lds(cidx));
.LBB0_1044:
	s_or_b64 exec, exec, s[0:1]
	v_mov_b32_e32 v2, s38
	ds_read2st64_b32 v[0:1], v35 offset1:2
	ds_read_b32 v4, v2
	s_waitcnt lgkmcnt(1)
	v_mov_b32_e32 v6, v1
	s_waitcnt lgkmcnt(0)
	v_sub_f32_e32 v2, v4, v0
	v_mul_f32_e32 v2, 0x3fb8aa3b, v2
	v_pk_mul_f32 v[0:1], v[82:83], v[6:7] op_sel_hi:[1,0]
	v_exp_f32_e32 v5, v2
	v_pk_mul_f32 v[2:3], v[78:79], v[6:7] op_sel_hi:[1,0]
	v_cvt_pk_bf16_f32 v0, v0, v1
	v_cvt_pk_bf16_f32 v1, v2, v3
	v_pk_mul_f32 v[2:3], v[74:75], v[6:7] op_sel_hi:[1,0]
	v_pk_mul_f32 v[8:9], v[70:71], v[6:7] op_sel_hi:[1,0]
	v_cvt_pk_bf16_f32 v2, v2, v3
	v_cvt_pk_bf16_f32 v3, v8, v9
	ds_write_b128 v34, v[0:3] offset:17408
	v_pk_mul_f32 v[0:1], v[80:81], v[6:7] op_sel_hi:[1,0]
	v_pk_mul_f32 v[2:3], v[76:77], v[6:7] op_sel_hi:[1,0]
	v_cvt_pk_bf16_f32 v0, v0, v1
	v_cvt_pk_bf16_f32 v1, v2, v3
	v_pk_mul_f32 v[2:3], v[72:73], v[6:7] op_sel_hi:[1,0]
	v_pk_mul_f32 v[6:7], v[68:69], v[6:7] op_sel_hi:[1,0]
	v_cvt_pk_bf16_f32 v2, v2, v3
	v_cvt_pk_bf16_f32 v3, v6, v7
	ds_write_b128 v34, v[0:3] offset:17424
	v_lshlrev_b32_e32 v0, 1, v63
	v_mul_f32_e32 v1, v66, v5
	v_mul_u32_u24_e32 v2, 0x90, v162
	v_cvt_pk_bf16_f32 v1, v1, s0
	v_add3_u32 v0, 0, v0, v2
	ds_write_b16 v0, v1 offset:34816
	v_mul_f32_e32 v1, v67, v5
	v_cvt_pk_bf16_f32 v1, v1, s0
	ds_write_b16 v0, v1 offset:34960
	v_mul_f32_e32 v1, v96, v5
	v_cvt_pk_bf16_f32 v1, v1, s0
	ds_write_b16 v0, v1 offset:35104
	v_mul_f32_e32 v1, v97, v5
	v_cvt_pk_bf16_f32 v1, v1, s0
	ds_write_b16 v0, v1 offset:35248
	v_mul_f32_e32 v1, v94, v5
	v_cvt_pk_bf16_f32 v1, v1, s0
	ds_write_b16 v0, v1 offset:35392
	v_mul_f32_e32 v1, v95, v5
	v_cvt_pk_bf16_f32 v1, v1, s0
	ds_write_b16 v0, v1 offset:35536
	v_mul_f32_e32 v1, v92, v5
	v_cvt_pk_bf16_f32 v1, v1, s0
	ds_write_b16 v0, v1 offset:35680
	v_mul_f32_e32 v1, v93, v5
	v_cvt_pk_bf16_f32 v1, v1, s0
	ds_write_b16 v0, v1 offset:35824
	v_mul_f32_e32 v1, v90, v5
	v_cvt_pk_bf16_f32 v1, v1, s0
	ds_write_b16 v0, v1 offset:35968
	v_mul_f32_e32 v1, v91, v5
	v_cvt_pk_bf16_f32 v1, v1, s0
	ds_write_b16 v0, v1 offset:36112
	v_mul_f32_e32 v1, v88, v5
	v_cvt_pk_bf16_f32 v1, v1, s0
	ds_write_b16 v0, v1 offset:36256
	v_mul_f32_e32 v1, v89, v5
	v_cvt_pk_bf16_f32 v1, v1, s0
	ds_write_b16 v0, v1 offset:36400
	v_mul_f32_e32 v1, v86, v5
	v_cvt_pk_bf16_f32 v1, v1, s0
	ds_write_b16 v0, v1 offset:36544
	v_mul_f32_e32 v1, v87, v5
	v_cvt_pk_bf16_f32 v1, v1, s0
	ds_write_b16 v0, v1 offset:36688
	v_mul_f32_e32 v1, v84, v5
	v_cvt_pk_bf16_f32 v1, v1, s0
	ds_write_b16 v0, v1 offset:36832
	v_mul_f32_e32 v1, v85, v5
	v_cvt_pk_bf16_f32 v1, v1, s0
	ds_write_b16 v0, v1 offset:36976
	v_mov_b32_e32 v0, v224
	s_movk_i32 s0, 0x1200
	v_cmp_ngt_f32_e32 vcc, s92, v4
	v_cmp_nlt_f32_e64 s[2:3], s93, v4
	s_waitcnt lgkmcnt(0)
	s_barrier
	s_nop 0
	v_cmp_gt_i32_e64 s[0:1], s0, v0
	s_and_saveexec_b64 s[4:5], s[0:1]
	s_cbranch_execz .LBB0_1059
	s_mul_i32 s0, s96, 0x12000
	s_mul_hi_i32 s1, s96, 0x12000
	s_add_u32 s0, s26, s0
	v_ashrrev_i32_e32 v1, 31, v0
	s_addc_u32 s1, s27, s1
	v_lshlrev_b32_e32 v5, 4, v0
	v_lshl_add_u64 v[2:3], v[0:1], 4, s[0:1]
	v_lshrrev_b32_e32 v220, 4, v224
	v_mul_u32_u24_e32 v220, 0x110, v220
	v_and_b32_e32 v223, 15, v224
	v_lshl_add_u32 v220, v223, 4, v220
	v_lshrrev_b32_e32 v221, 3, v224
	v_mul_u32_u24_e32 v221, 0x90, v221
	v_and_b32_e32 v223, 7, v224
	v_lshl_add_u32 v221, v223, 4, v221
	v_add_u32_e32 v222, 0x2400, v221
	ds_read_b128 v[184:187], v220
	ds_read_b128 v[188:191], v220 offset:8704
	ds_read_b128 v[192:195], v220 offset:17408
	ds_read_b128 v[196:199], v220 offset:26112
	ds_read_b128 v[200:203], v221 offset:34816
	ds_read_b128 v[204:207], v221 offset:44032
	ds_read_b128 v[208:211], v221 offset:53248
	ds_read_b128 v[212:215], v221 offset:62464
	ds_read_b128 v[6:9], v222 offset:62464
	s_waitcnt lgkmcnt(8)
	global_store_dwordx4 v[2:3], v[184:187], off
	v_lshl_add_u64 v[2:3], v[2:3], 0, s[94:95]
	s_waitcnt lgkmcnt(7)
	global_store_dwordx4 v[2:3], v[188:191], off
	v_lshl_add_u64 v[2:3], v[2:3], 0, s[94:95]
	s_waitcnt lgkmcnt(6)
	global_store_dwordx4 v[2:3], v[192:195], off
	v_lshl_add_u64 v[2:3], v[2:3], 0, s[94:95]
	s_waitcnt lgkmcnt(5)
	global_store_dwordx4 v[2:3], v[196:199], off
	v_lshl_add_u64 v[2:3], v[2:3], 0, s[94:95]
	s_waitcnt lgkmcnt(4)
	global_store_dwordx4 v[2:3], v[200:203], off
	v_lshl_add_u64 v[2:3], v[2:3], 0, s[94:95]
	s_waitcnt lgkmcnt(3)
	global_store_dwordx4 v[2:3], v[204:207], off
	v_lshl_add_u64 v[2:3], v[2:3], 0, s[94:95]
	s_waitcnt lgkmcnt(2)
	global_store_dwordx4 v[2:3], v[208:211], off
	v_lshl_add_u64 v[2:3], v[2:3], 0, s[94:95]
	s_waitcnt lgkmcnt(1)
	global_store_dwordx4 v[2:3], v[212:215], off
	v_lshl_add_u64 v[2:3], v[2:3], 0, s[94:95]
	s_waitcnt lgkmcnt(0)
	global_store_dwordx4 v[2:3], v[6:9], off

; __device__ __forceinline__ int opq(int x) { asm volatile("" : "+v"(x)); return x; }
; __device__ __forceinline__ float delta_prep(const Params& p, int l, int h, bool isP, int grow0, int t0, int nvalid, int bb, char* sm) {
;     ...
;   {
;     const float eg = misc[128 + rl];
;     const float ek = __expf(Glast - misc[rl]);
;     bfraw* qg = (bfraw*)(sm + L_QG);
;     bfraw* kgT = (bfraw*)(sm + L_KGT);
;     float t[16];
; #pragma unroll
;     for (int e = 0; e < 16; ++e) t[e] = qf[e] * eg;
;     *(uint4*)(qg + rl * 136 + cg8 * 16) = pack8(t); *(uint4*)(qg + rl * 136 + cg8 * 16 + 8) = pack8(t + 8);
; #pragma unroll
;     for (int e = 0; e < 16; ++e) kgT[(cg8 * 16 + e) * 72 + rl] = f2bf(kf[e] * ek);
;   }
;   const float gl = expf(Glast);
;   __syncthreads();
; __device__ __forceinline__ void f1_unit(const Params& p, int l, int u, char* sm) {
;     ...
;   bfraw* D = (bfraw*)(p.ws + WS_D) + (size_t)u * DUNIT;
;   for (int cidx = opq(threadIdx.x); cidx < 4608; cidx += NTHR)
;     *(uint4*)(D + (size_t)cidx * 8) = *(const uint4*)(sm + dchunk_lds(cidx));
.LBB0_3802:
	s_or_b64 exec, exec, s[0:1]
	v_mov_b32_e32 v2, s50
	ds_read2st64_b32 v[0:1], v35 offset1:2
	ds_read_b32 v4, v2
	s_waitcnt lgkmcnt(1)
	v_mov_b32_e32 v6, v1
	s_waitcnt lgkmcnt(0)
	v_sub_f32_e32 v2, v4, v0
	v_mul_f32_e32 v2, 0x3fb8aa3b, v2
	v_pk_mul_f32 v[0:1], v[82:83], v[6:7] op_sel_hi:[1,0]
	v_exp_f32_e32 v5, v2
	v_pk_mul_f32 v[2:3], v[78:79], v[6:7] op_sel_hi:[1,0]
	v_cvt_pk_bf16_f32 v0, v0, v1
	v_cvt_pk_bf16_f32 v1, v2, v3
	v_pk_mul_f32 v[2:3], v[74:75], v[6:7] op_sel_hi:[1,0]
	v_pk_mul_f32 v[8:9], v[70:71], v[6:7] op_sel_hi:[1,0]
	v_cvt_pk_bf16_f32 v2, v2, v3
	v_cvt_pk_bf16_f32 v3, v8, v9
	ds_write_b128 v34, v[0:3] offset:17408
	v_pk_mul_f32 v[0:1], v[80:81], v[6:7] op_sel_hi:[1,0]
	v_pk_mul_f32 v[2:3], v[76:77], v[6:7] op_sel_hi:[1,0]
	v_cvt_pk_bf16_f32 v0, v0, v1
	v_cvt_pk_bf16_f32 v1, v2, v3
	v_pk_mul_f32 v[2:3], v[72:73], v[6:7] op_sel_hi:[1,0]
	v_pk_mul_f32 v[6:7], v[68:69], v[6:7] op_sel_hi:[1,0]
	v_cvt_pk_bf16_f32 v2, v2, v3
	v_cvt_pk_bf16_f32 v3, v6, v7
	ds_write_b128 v34, v[0:3] offset:17424
	v_lshlrev_b32_e32 v0, 1, v63
	v_mul_f32_e32 v1, v66, v5
	v_mul_u32_u24_e32 v2, 0x90, v162
	v_cvt_pk_bf16_f32 v1, v1, s0
	v_add3_u32 v0, 0, v0, v2
	ds_write_b16 v0, v1 offset:34816
	v_mul_f32_e32 v1, v67, v5
	v_cvt_pk_bf16_f32 v1, v1, s0
	ds_write_b16 v0, v1 offset:34960
	v_mul_f32_e32 v1, v96, v5
	v_cvt_pk_bf16_f32 v1, v1, s0
	ds_write_b16 v0, v1 offset:35104
	v_mul_f32_e32 v1, v97, v5
	v_cvt_pk_bf16_f32 v1, v1, s0
	ds_write_b16 v0, v1 offset:35248
	v_mul_f32_e32 v1, v94, v5
	v_cvt_pk_bf16_f32 v1, v1, s0
	ds_write_b16 v0, v1 offset:35392
	v_mul_f32_e32 v1, v95, v5
	v_cvt_pk_bf16_f32 v1, v1, s0
	ds_write_b16 v0, v1 offset:35536
	v_mul_f32_e32 v1, v92, v5
	v_cvt_pk_bf16_f32 v1, v1, s0
	ds_write_b16 v0, v1 offset:35680
	v_mul_f32_e32 v1, v93, v5
	v_cvt_pk_bf16_f32 v1, v1, s0
	ds_write_b16 v0, v1 offset:35824
	v_mul_f32_e32 v1, v90, v5
	v_cvt_pk_bf16_f32 v1, v1, s0
	ds_write_b16 v0, v1 offset:35968
	v_mul_f32_e32 v1, v91, v5
	v_cvt_pk_bf16_f32 v1, v1, s0
	ds_write_b16 v0, v1 offset:36112
	v_mul_f32_e32 v1, v88, v5
	v_cvt_pk_bf16_f32 v1, v1, s0
	ds_write_b16 v0, v1 offset:36256
	v_mul_f32_e32 v1, v89, v5
	v_cvt_pk_bf16_f32 v1, v1, s0
	ds_write_b16 v0, v1 offset:36400
	v_mul_f32_e32 v1, v86, v5
	v_cvt_pk_bf16_f32 v1, v1, s0
	ds_write_b16 v0, v1 offset:36544
	v_mul_f32_e32 v1, v87, v5
	v_cvt_pk_bf16_f32 v1, v1, s0
	ds_write_b16 v0, v1 offset:36688
	v_mul_f32_e32 v1, v84, v5
	v_cvt_pk_bf16_f32 v1, v1, s0
	ds_write_b16 v0, v1 offset:36832
	v_mul_f32_e32 v1, v85, v5
	v_cvt_pk_bf16_f32 v1, v1, s0
	ds_write_b16 v0, v1 offset:36976
	v_mov_b32_e32 v0, v224
	s_movk_i32 s0, 0x1200
	v_cmp_ngt_f32_e32 vcc, s92, v4
	v_cmp_nlt_f32_e64 s[2:3], s93, v4
	s_waitcnt lgkmcnt(0)
	s_barrier
	s_nop 0
	v_cmp_gt_i32_e64 s[0:1], s0, v0
	s_and_saveexec_b64 s[4:5], s[0:1]
	s_cbranch_execz .LBB0_3817
	s_mul_i32 s0, s44, 0x12000
	s_mul_hi_i32 s1, s44, 0x12000
	s_add_u32 s0, s54, s0
	v_ashrrev_i32_e32 v1, 31, v0
	s_addc_u32 s1, s66, s1
	v_lshlrev_b32_e32 v5, 4, v0
	v_lshl_add_u64 v[2:3], v[0:1], 4, s[0:1]
	v_lshrrev_b32_e32 v220, 4, v224
	v_mul_u32_u24_e32 v220, 0x110, v220
	v_and_b32_e32 v223, 15, v224
	v_lshl_add_u32 v220, v223, 4, v220
	v_lshrrev_b32_e32 v221, 3, v224
	v_mul_u32_u24_e32 v221, 0x90, v221
	v_and_b32_e32 v223, 7, v224
	v_lshl_add_u32 v221, v223, 4, v221
	v_add_u32_e32 v222, 0x2400, v221
	ds_read_b128 v[184:187], v220
	ds_read_b128 v[188:191], v220 offset:8704
	ds_read_b128 v[192:195], v220 offset:17408
	ds_read_b128 v[196:199], v220 offset:26112
	ds_read_b128 v[200:203], v221 offset:34816
	ds_read_b128 v[204:207], v221 offset:44032
	ds_read_b128 v[208:211], v221 offset:53248
	ds_read_b128 v[212:215], v221 offset:62464
	ds_read_b128 v[6:9], v222 offset:62464
	s_waitcnt lgkmcnt(8)
	global_store_dwordx4 v[2:3], v[184:187], off
	v_lshl_add_u64 v[2:3], v[2:3], 0, s[42:43]
	s_waitcnt lgkmcnt(7)
	global_store_dwordx4 v[2:3], v[188:191], off
	v_lshl_add_u64 v[2:3], v[2:3], 0, s[42:43]
	s_waitcnt lgkmcnt(6)
	global_store_dwordx4 v[2:3], v[192:195], off
	v_lshl_add_u64 v[2:3], v[2:3], 0, s[42:43]
	s_waitcnt lgkmcnt(5)
	global_store_dwordx4 v[2:3], v[196:199], off
	v_lshl_add_u64 v[2:3], v[2:3], 0, s[42:43]
	s_waitcnt lgkmcnt(4)
	global_store_dwordx4 v[2:3], v[200:203], off
	v_lshl_add_u64 v[2:3], v[2:3], 0, s[42:43]
	s_waitcnt lgkmcnt(3)
	global_store_dwordx4 v[2:3], v[204:207], off
	v_lshl_add_u64 v[2:3], v[2:3], 0, s[42:43]
	s_waitcnt lgkmcnt(2)
	global_store_dwordx4 v[2:3], v[208:211], off
	v_lshl_add_u64 v[2:3], v[2:3], 0, s[42:43]
	s_waitcnt lgkmcnt(1)
	global_store_dwordx4 v[2:3], v[212:215], off
	v_lshl_add_u64 v[2:3], v[2:3], 0, s[42:43]
	s_waitcnt lgkmcnt(0)
	global_store_dwordx4 v[2:3], v[6:9], off
